# P11 attention QK: K-fragment LDS reads pipelined through a 4-buffer ring with counted lgkmcnt (v57 + attnqk)
# speedup vs baseline: 1.0110x; 1.0040x over previous
.LBB0_1340:
	v_cmp_eq_f32_e32 vcc, 0, v171
	s_nop 1
	s_cmp_eq_u64 vcc, exec
	s_cbranch_scc1 .LBB0_1346
	s_cmp_ge_i32 s12, s40
	s_cbranch_scc1 .LBB0_1346
	ds_read_b128 v[2:5], v204 offset:16384
	ds_read_b128 v[6:9], v204 offset:24576
	ds_read_b128 v[10:13], v205 offset:16384
	ds_read_b128 v[250:253], v205 offset:24576
	s_or_b32 s13, s12, 63
	s_mov_b64 s[10:11], -1
	s_cmp_lt_i32 s13, s39
	s_waitcnt lgkmcnt(3)
	v_mfma_f32_32x32x16_bf16 v[80:95], v[2:5], v[112:115], 0
	v_mbcnt_hi_u32_b32 v173, -1, v214
	ds_read_b128 v[2:5], v206 offset:16384
	s_waitcnt lgkmcnt(3)
	v_mfma_f32_32x32x16_bf16 v[96:111], v[6:9], v[112:115], 0
	ds_read_b128 v[6:9], v206 offset:24576
	s_waitcnt lgkmcnt(3)
	v_mfma_f32_32x32x16_bf16 v[80:95], v[10:13], v[116:119], v[80:95]
	ds_read_b128 v[10:13], v207 offset:16384
	s_waitcnt lgkmcnt(3)
	v_mfma_f32_32x32x16_bf16 v[96:111], v[250:253], v[116:119], v[96:111]
	ds_read_b128 v[250:253], v207 offset:24576
	s_waitcnt lgkmcnt(3)
	v_mfma_f32_32x32x16_bf16 v[80:95], v[2:5], v[120:123], v[80:95]
	ds_read_b128 v[2:5], v208 offset:16384
	s_waitcnt lgkmcnt(3)
	v_mfma_f32_32x32x16_bf16 v[96:111], v[6:9], v[120:123], v[96:111]
	ds_read_b128 v[6:9], v208 offset:24576
	s_waitcnt lgkmcnt(3)
	v_mfma_f32_32x32x16_bf16 v[80:95], v[10:13], v[124:127], v[80:95]
	ds_read_b128 v[10:13], v209 offset:24576
	s_waitcnt lgkmcnt(3)
	v_mfma_f32_32x32x16_bf16 v[96:111], v[250:253], v[124:127], v[96:111]
	ds_read_b128 v[250:253], v210 offset:24576
	s_waitcnt lgkmcnt(3)
	v_mfma_f32_32x32x16_bf16 v[80:95], v[2:5], v[128:131], v[80:95]
	ds_read_b128 v[2:5], v209 offset:16384
	s_waitcnt lgkmcnt(3)
	v_mfma_f32_32x32x16_bf16 v[96:111], v[6:9], v[128:131], v[96:111]
	ds_read_b128 v[6:9], v211 offset:24576
	s_waitcnt lgkmcnt(3)
	v_mfma_f32_32x32x16_bf16 v[96:111], v[10:13], v[132:135], v[96:111]
	ds_read_b128 v[10:13], v210 offset:16384
	s_waitcnt lgkmcnt(3)
	v_mfma_f32_32x32x16_bf16 v[96:111], v[250:253], v[136:139], v[96:111]
	ds_read_b128 v[250:253], v211 offset:16384
	s_waitcnt lgkmcnt(3)
	v_mfma_f32_32x32x16_bf16 v[80:95], v[2:5], v[132:135], v[80:95]
	s_waitcnt lgkmcnt(2)
	v_mfma_f32_32x32x16_bf16 v[96:111], v[6:9], v[140:143], v[96:111]
	s_waitcnt lgkmcnt(1)
	v_mfma_f32_32x32x16_bf16 v[80:95], v[10:13], v[136:139], v[80:95]
	s_nop 8
	v_max_f32_e32 v224, v96, v96
	v_max_f32_e32 v223, v97, v97
	v_max_f32_e32 v222, v98, v98
	v_max_f32_e32 v221, v99, v99
	v_max_f32_e32 v220, v100, v100
	v_max_f32_e32 v219, v101, v101
	v_max_f32_e32 v218, v102, v102
	s_waitcnt lgkmcnt(0)
	v_mfma_f32_32x32x16_bf16 v[80:95], v[250:253], v[140:143], v[80:95]
	v_max_f32_e32 v217, v103, v103
	v_max_f32_e32 v216, v104, v104
	v_max_f32_e32 v215, v105, v105
	v_max_f32_e32 v185, v106, v106
	v_max_f32_e32 v183, v107, v107
	v_max_f32_e32 v181, v108, v108
	v_max_f32_e32 v179, v109, v109
	v_max_f32_e32 v177, v110, v110
	v_max_f32_e32 v175, v111, v111
	s_nop 2
	v_max_f32_e32 v111, v80, v80
	v_max_f32_e32 v109, v81, v81
	v_max_f32_e32 v110, v82, v82
	v_max_f32_e32 v108, v83, v83
	v_max_f32_e32 v107, v84, v84
	v_max_f32_e32 v106, v85, v85
	v_max_f32_e32 v105, v86, v86
	v_max_f32_e32 v104, v87, v87
	v_max_f32_e32 v103, v88, v88
	v_max_f32_e32 v102, v89, v89
	v_max_f32_e32 v101, v90, v90
	v_max_f32_e32 v100, v91, v91
	v_max_f32_e32 v99, v92, v92
	v_max_f32_e32 v98, v93, v93
	v_max_f32_e32 v82, v94, v94
	v_max_f32_e32 v1, v95, v95
	s_cbranch_scc1 .LBB0_1343
	v_min_f32_e32 v2, 0x42c80000, v224
	v_exp_f32_e32 v2, v2
	v_min_f32_e32 v3, 0x42c80000, v223
	v_exp_f32_e32 v3, v3
	v_or_b32_e32 v90, s12, v196
	v_add_f32_e32 v4, 1.0, v2
	v_rcp_f32_e32 v4, v4
	v_or_b32_e32 v5, 32, v90
	v_cmp_lt_i32_e32 vcc, v5, v186
	v_min_f32_e32 v5, 0x42c80000, v222
	v_mul_f32_e32 v2, v2, v4
	v_cndmask_b32_e32 v83, 0, v2, vcc
	v_add_f32_e32 v2, 1.0, v3
	v_rcp_f32_e32 v2, v2
	v_exp_f32_e32 v5, v5
	v_cndmask_b32_e32 v11, 1.0, v4, vcc
	v_or_b32_e32 v4, 33, v90
	v_cmp_lt_i32_e32 vcc, v4, v186
	v_min_f32_e32 v4, 0x42c80000, v221
	v_exp_f32_e32 v4, v4
	v_cndmask_b32_e32 v15, 1.0, v2, vcc
	v_mul_f32_e32 v2, v3, v2
	v_cndmask_b32_e32 v88, 0, v2, vcc
	v_add_f32_e32 v2, 1.0, v5
	v_rcp_f32_e32 v2, v2
	v_or_b32_e32 v3, 34, v90
	v_cmp_lt_i32_e32 vcc, v3, v186
	v_or_b32_e32 v3, 35, v90
	v_min_f32_e32 v97, 0x42c80000, v175
	v_cndmask_b32_e32 v81, 1.0, v2, vcc
	v_mul_f32_e32 v2, v5, v2
	v_cndmask_b32_e32 v89, 0, v2, vcc
	v_add_f32_e32 v2, 1.0, v4
	v_rcp_f32_e32 v2, v2
	v_min_f32_e32 v5, 0x42c80000, v220
	v_exp_f32_e32 v5, v5
	v_cmp_lt_i32_e32 vcc, v3, v186
	v_or_b32_e32 v3, 40, v90
	v_exp_f32_e32 v97, v97
	v_cndmask_b32_e32 v85, 1.0, v2, vcc
	v_mul_f32_e32 v2, v4, v2
	v_cndmask_b32_e32 v91, 0, v2, vcc
	v_add_f32_e32 v2, 1.0, v5
	v_rcp_f32_e32 v2, v2
	v_min_f32_e32 v4, 0x42c80000, v219
	v_exp_f32_e32 v4, v4
	v_cmp_lt_i32_e32 vcc, v3, v186
	v_or_b32_e32 v3, 41, v90
	v_add_f32_e32 v227, 1.0, v97
	v_cndmask_b32_e32 v8, 1.0, v2, vcc
	v_mul_f32_e32 v2, v5, v2
	v_cndmask_b32_e32 v92, 0, v2, vcc
	v_add_f32_e32 v2, 1.0, v4
	v_rcp_f32_e32 v2, v2
	v_min_f32_e32 v5, 0x42c80000, v218
	v_exp_f32_e32 v5, v5
	v_cmp_lt_i32_e32 vcc, v3, v186
	v_or_b32_e32 v3, 42, v90
	v_rcp_f32_e32 v227, v227
	v_cndmask_b32_e32 v86, 1.0, v2, vcc
	v_mul_f32_e32 v2, v4, v2
	v_cndmask_b32_e32 v93, 0, v2, vcc
	v_add_f32_e32 v2, 1.0, v5
	v_rcp_f32_e32 v2, v2
	v_min_f32_e32 v4, 0x42c80000, v217
	v_exp_f32_e32 v4, v4
	v_cmp_lt_i32_e32 vcc, v3, v186
	v_or_b32_e32 v3, 43, v90
	v_and_b32_e32 v230, 64, v173
	v_cndmask_b32_e32 v87, 1.0, v2, vcc
	v_mul_f32_e32 v2, v5, v2
	v_cndmask_b32_e32 v94, 0, v2, vcc
	v_add_f32_e32 v2, 1.0, v4
	v_rcp_f32_e32 v2, v2
	v_min_f32_e32 v5, 0x42c80000, v216
	v_exp_f32_e32 v5, v5
	v_cmp_lt_i32_e32 vcc, v3, v186
	v_or_b32_e32 v3, 48, v90
	v_or_b32_e32 v226, 58, v90
	v_cndmask_b32_e32 v95, 1.0, v2, vcc
	v_mul_f32_e32 v2, v4, v2
	v_cndmask_b32_e32 v96, 0, v2, vcc
	v_add_f32_e32 v2, 1.0, v5
	v_rcp_f32_e32 v2, v2
	v_min_f32_e32 v4, 0x42c80000, v215
	v_exp_f32_e32 v4, v4
	v_cmp_lt_i32_e32 vcc, v3, v186
	v_or_b32_e32 v3, 49, v90
	v_or_b32_e32 v228, 59, v90
	v_cndmask_b32_e32 v6, 1.0, v2, vcc
	v_mul_f32_e32 v2, v5, v2
	v_cndmask_b32_e32 v12, 0, v2, vcc
	v_add_f32_e32 v2, 1.0, v4
	v_rcp_f32_e32 v2, v2
	v_min_f32_e32 v5, 0x42c80000, v185
	v_exp_f32_e32 v5, v5
	v_cmp_lt_i32_e32 vcc, v3, v186
	v_or_b32_e32 v3, 50, v90
	v_xor_b32_e32 v229, 32, v173
	v_cndmask_b32_e32 v7, 1.0, v2, vcc
	v_mul_f32_e32 v2, v4, v2
	v_cndmask_b32_e32 v9, 0, v2, vcc
	v_add_f32_e32 v2, 1.0, v5
	v_rcp_f32_e32 v2, v2
	v_min_f32_e32 v4, 0x42c80000, v183
	v_exp_f32_e32 v4, v4
	v_cmp_lt_i32_e32 vcc, v3, v186
	v_or_b32_e32 v3, 51, v90
	v_add_u32_e32 v230, 64, v230
	v_cndmask_b32_e32 v10, 1.0, v2, vcc
	v_mul_f32_e32 v2, v5, v2
	v_cndmask_b32_e32 v13, 0, v2, vcc
	v_add_f32_e32 v2, 1.0, v4
	v_rcp_f32_e32 v2, v2
	v_min_f32_e32 v5, 0x42c80000, v181
	v_exp_f32_e32 v5, v5
	v_cmp_lt_i32_e32 vcc, v3, v186
	v_or_b32_e32 v3, 56, v90
	v_cmp_lt_i32_e64 s[10:11], v228, v186
	v_cndmask_b32_e32 v14, 1.0, v2, vcc
	v_mul_f32_e32 v2, v4, v2
	v_cndmask_b32_e32 v84, 0, v2, vcc
	v_add_f32_e32 v2, 1.0, v5
	v_min_f32_e32 v4, 0x42c80000, v179
	v_rcp_f32_e32 v2, v2
	v_exp_f32_e32 v4, v4
	v_cmp_lt_i32_e32 vcc, v3, v186
	v_cmp_lt_i32_e64 s[12:13], v229, v230
	v_cndmask_b32_e64 v228, 1.0, v227, s[10:11]
	v_cndmask_b32_e32 v3, 1.0, v2, vcc
	v_mul_f32_e32 v2, v5, v2
	v_add_f32_e32 v5, 1.0, v4
	v_rcp_f32_e32 v5, v5
	v_cndmask_b32_e32 v80, 0, v2, vcc
	v_or_b32_e32 v2, 57, v90
	v_cmp_lt_i32_e32 vcc, v2, v186
	v_mul_f32_e32 v4, v4, v5
	v_cndmask_b32_e64 v229, v173, v229, s[12:13]
	v_cndmask_b32_e32 v2, 1.0, v5, vcc
	v_min_f32_e32 v5, 0x42c80000, v177
	v_exp_f32_e32 v5, v5
	v_cndmask_b32_e32 v4, 0, v4, vcc
	v_cmp_lt_i32_e32 vcc, v226, v186
	v_lshlrev_b32_e32 v231, 2, v229
	v_add_f32_e32 v225, 1.0, v5
	v_rcp_f32_e32 v225, v225
	v_mul_f32_e32 v3, v3, v2
	v_mul_f32_e32 v8, v8, v86
	v_cndmask_b32_e32 v226, 1.0, v225, vcc
	v_mul_f32_e32 v229, v226, v228
	v_mul_f32_e32 v229, v3, v229
	ds_bpermute_b32 v230, v231, v229
	v_mul_f32_e32 v3, v5, v225
	v_cndmask_b32_e32 v5, 0, v3, vcc
	v_mul_f32_e32 v3, v97, v227
	v_cndmask_b32_e64 v3, 0, v3, s[10:11]
	s_waitcnt lgkmcnt(0)
	v_mul_f32_e32 v97, v171, v230
	v_cndmask_b32_e64 v97, v171, v97, s[6:7]
	v_mul_f32_e32 v225, v228, v97
	v_mul_f32_e32 v226, v226, v225
	v_mul_f32_e32 v227, v2, v226
	v_mul_f32_e32 v2, v5, v225
	v_mul_f32_e32 v5, v6, v7
	v_mul_f32_e32 v6, v10, v14
	v_mul_f32_e32 v3, v3, v97
	v_mul_f32_e32 v97, v5, v6
	ds_bpermute_b32 v225, v231, v97
	v_mul_f32_e32 v6, v229, v230
	v_mul_f32_e32 v5, v4, v226
	v_mul_f32_e32 v4, v80, v227
	v_mul_f32_e32 v80, v171, v6
	s_waitcnt lgkmcnt(0)
	v_mul_f32_e32 v6, v80, v225
	v_cndmask_b32_e64 v6, v80, v6, s[6:7]
	v_mul_f32_e32 v14, v14, v6
	v_mul_f32_e32 v226, v10, v14
	v_mul_f32_e32 v10, v87, v95
	v_mul_f32_e32 v10, v8, v10
	v_mul_f32_e32 v227, v7, v226
	v_mul_f32_e32 v7, v84, v6
	v_mul_f32_e32 v6, v13, v14
	ds_bpermute_b32 v14, v231, v10
	v_mul_f32_e32 v84, v97, v225
	v_mul_f32_e32 v8, v12, v227
	v_pk_mul_f32 v[12:13], v[80:81], v[84:85]
	v_cmp_lt_i32_e32 vcc, v90, v186
	s_waitcnt lgkmcnt(0)
	v_mul_f32_e32 v80, v12, v14
	v_cndmask_b32_e64 v80, v12, v80, s[6:7]
	v_mul_f32_e32 v84, v95, v80
	v_mul_f32_e32 v95, v87, v84
	v_pk_mul_f32 v[10:11], v[10:11], v[14:15]
	v_mul_f32_e32 v97, v86, v95
	v_pk_mul_f32 v[86:87], v[10:11], v[12:13]
	ds_bpermute_b32 v225, v231, v87
	v_mul_f32_e32 v11, v96, v80
	v_mul_f32_e32 v10, v94, v84
	v_mul_f32_e32 v9, v9, v226
	v_mul_f32_e32 v12, v92, v97
	s_waitcnt lgkmcnt(0)
	v_mul_f32_e32 v14, v86, v225
	v_cndmask_b32_e64 v14, v86, v14, s[6:7]
	v_mul_f32_e32 v80, v85, v14
	v_mul_f32_e32 v81, v81, v80
	v_mul_f32_e32 v84, v15, v81
	v_mul_f32_e32 v15, v91, v14
	v_mul_f32_e32 v14, v89, v80
	v_min_f32_e32 v80, 0x42c80000, v111
	v_exp_f32_e32 v85, v80
	v_mul_f32_e32 v80, v83, v84
	v_min_f32_e32 v84, 0x42c80000, v109
	v_exp_f32_e32 v84, v84
	v_add_f32_e32 v83, 1.0, v85
	v_rcp_f32_e32 v83, v83
	v_mul_f32_e32 v81, v88, v81
	v_mul_f32_e32 v88, v87, v225
	v_min_f32_e32 v87, 0x42c80000, v110
	v_cndmask_b32_e32 v245, 1.0, v83, vcc
	v_mul_f32_e32 v83, v85, v83
	v_cndmask_b32_e32 v225, 0, v83, vcc
	v_add_f32_e32 v83, 1.0, v84
	v_rcp_f32_e32 v85, v83
	v_exp_f32_e32 v87, v87
	v_or_b32_e32 v83, 1, v90
	v_cmp_lt_i32_e32 vcc, v83, v186
	v_mul_f32_e32 v84, v84, v85
	v_min_f32_e32 v89, 0x42c80000, v108
	v_cndmask_b32_e32 v230, 0, v84, vcc
	v_add_f32_e32 v84, 1.0, v87
	v_rcp_f32_e32 v84, v84
	v_cndmask_b32_e32 v83, 1.0, v85, vcc
	v_or_b32_e32 v85, 2, v90
	v_exp_f32_e32 v89, v89
	v_cmp_lt_i32_e32 vcc, v85, v186
	v_or_b32_e32 v85, 3, v90
	v_mul_f32_e32 v13, v93, v95
	v_cndmask_b32_e32 v226, 1.0, v84, vcc
	v_mul_f32_e32 v84, v87, v84
	v_min_f32_e32 v87, 0x42c80000, v107
	v_exp_f32_e32 v87, v87
	v_cndmask_b32_e32 v227, 0, v84, vcc
	v_add_f32_e32 v84, 1.0, v89
	v_rcp_f32_e32 v84, v84
	v_cmp_lt_i32_e32 vcc, v85, v186
	v_add_f32_e32 v85, 1.0, v87
	v_rcp_f32_e32 v85, v85
	v_cndmask_b32_e32 v228, 1.0, v84, vcc
	v_mul_f32_e32 v84, v89, v84
	v_cndmask_b32_e32 v229, 0, v84, vcc
	v_or_b32_e32 v84, 8, v90
	v_cmp_lt_i32_e32 vcc, v84, v186
	v_mul_f32_e32 v84, v87, v85
	v_or_b32_e32 v89, 11, v90
	v_cndmask_b32_e32 v97, 1.0, v85, vcc
	v_min_f32_e32 v85, 0x42c80000, v106
	v_exp_f32_e32 v92, v85
	v_min_f32_e32 v85, 0x42c80000, v105
	v_cndmask_b32_e32 v96, 0, v84, vcc
	v_exp_f32_e32 v93, v85
	v_add_f32_e32 v84, 1.0, v92
	v_rcp_f32_e32 v94, v84
	v_min_f32_e32 v84, 0x42c80000, v104
	v_exp_f32_e32 v84, v84
	v_min_f32_e32 v85, 0x42c80000, v103
	v_exp_f32_e32 v85, v85
	v_add_f32_e32 v87, 1.0, v93
	v_rcp_f32_e32 v95, v87
	v_add_f32_e32 v87, 1.0, v84
	v_rcp_f32_e32 v232, v87
	v_add_f32_e32 v87, 1.0, v85
	v_rcp_f32_e32 v233, v87
	v_or_b32_e32 v87, 16, v90
	v_cmp_lt_i32_e64 s[10:11], v87, v169
	v_min_f32_e32 v87, 0x42c80000, v100
	v_exp_f32_e32 v238, v87
	v_min_f32_e32 v87, 0x42c80000, v99
	v_exp_f32_e32 v239, v87
	v_cmp_lt_i32_e32 vcc, v89, v186
	v_add_f32_e32 v87, 1.0, v238
	v_rcp_f32_e32 v240, v87
	v_add_f32_e32 v87, 1.0, v239
	v_rcp_f32_e32 v241, v87
	v_pk_mul_f32 v[84:85], v[84:85], v[232:233]
	v_or_b32_e32 v89, 19, v90
	v_cndmask_b32_e32 v247, 1.0, v232, vcc
	v_cndmask_b32_e32 v232, 0, v84, vcc
	v_or_b32_e32 v87, 24, v90
	v_cmp_lt_i32_e32 vcc, v89, v186
	v_min_f32_e32 v91, 0x42c80000, v98
	v_cndmask_b32_e64 v235, 1.0, v233, s[10:11]
	v_cndmask_b32_e64 v233, 0, v85, s[10:11]
	v_cndmask_b32_e32 v89, 1.0, v240, vcc
	v_cmp_lt_i32_e64 s[10:11], v87, v169
	v_pk_mul_f32 v[238:239], v[238:239], v[240:241]
	v_exp_f32_e32 v240, v91
	v_min_f32_e32 v91, 0x42c80000, v82
	v_cndmask_b32_e64 v87, 1.0, v241, s[10:11]
	v_exp_f32_e32 v241, v91
	v_min_f32_e32 v91, 0x42c80000, v1
	v_exp_f32_e32 v91, v91
	v_add_f32_e32 v234, 1.0, v240
	v_rcp_f32_e32 v242, v234
	v_add_f32_e32 v234, 1.0, v241
	v_add_f32_e32 v243, 1.0, v91
	v_rcp_f32_e32 v244, v243
	v_min_f32_e32 v85, 0x42c80000, v102
	v_rcp_f32_e32 v243, v234
	v_or_b32_e32 v234, 27, v90
	v_exp_f32_e32 v236, v85
	v_min_f32_e32 v85, 0x42c80000, v101
	v_cndmask_b32_e32 v238, 0, v238, vcc
	v_cmp_lt_i32_e32 vcc, v234, v186
	v_mul_f32_e32 v91, v91, v244
	v_exp_f32_e32 v237, v85
	v_cndmask_b32_e32 v248, 1.0, v244, vcc
	v_cndmask_b32_e32 v244, 0, v91, vcc
	v_or_b32_e32 v91, 26, v90
	v_or_b32_e32 v234, 25, v90
	v_cndmask_b32_e64 v239, 0, v239, s[10:11]
	v_cmp_lt_i32_e32 vcc, v234, v186
	v_cmp_lt_i32_e64 s[10:11], v91, v169
	v_add_f32_e32 v84, 1.0, v236
	v_cndmask_b32_e32 v249, 1.0, v242, vcc
	v_cndmask_b32_e64 v91, 1.0, v243, s[10:11]
	v_mul_f32_e32 v87, v87, v249
	v_mul_f32_e32 v234, v91, v248
	v_add_f32_e32 v85, 1.0, v237
	v_mul_f32_e32 v234, v87, v234
	v_rcp_f32_e32 v84, v84
	v_rcp_f32_e32 v85, v85
	v_pk_mul_f32 v[240:241], v[240:241], v[242:243]
	ds_bpermute_b32 v242, v231, v234
	v_or_b32_e32 v87, 18, v90
	v_or_b32_e32 v243, 17, v90
	v_cndmask_b32_e64 v241, 0, v241, s[10:11]
	v_cndmask_b32_e32 v240, 0, v240, vcc
	v_cmp_lt_i32_e32 vcc, v243, v186
	v_cmp_lt_i32_e64 s[10:11], v87, v169
	v_pk_mul_f32 v[92:93], v[92:93], v[94:95]
	v_cndmask_b32_e32 v243, 1.0, v84, vcc
	v_cndmask_b32_e64 v87, 1.0, v85, s[10:11]
	v_pk_mul_f32 v[84:85], v[236:237], v[84:85]
	s_waitcnt lgkmcnt(0)
	v_pk_mul_f32 v[234:235], v[234:235], v[242:243]
	v_cndmask_b32_e64 v237, 0, v85, s[10:11]
	v_cndmask_b32_e32 v236, 0, v84, vcc
	v_pk_mul_f32 v[84:85], v[86:87], v[88:89]
	v_mul_f32_e32 v245, v245, v83
	v_pk_mul_f32 v[234:235], v[234:235], v[84:85]
	v_mul_f32_e32 v86, v84, v242
	ds_bpermute_b32 v242, v231, v235
	v_cndmask_b32_e64 v246, v84, v86, s[6:7]
	v_mul_f32_e32 v85, v248, v246
	v_mul_f32_e32 v84, v91, v85
	v_mul_f32_e32 v249, v249, v84
	s_waitcnt lgkmcnt(0)
	v_mul_f32_e32 v86, v234, v242
	v_cndmask_b32_e64 v248, v234, v86, s[6:7]
	v_mul_f32_e32 v89, v89, v248
	v_mul_f32_e32 v88, v87, v89
	v_mul_f32_e32 v91, v243, v88
	v_pk_mul_f32 v[88:89], v[236:237], v[88:89]
	v_or_b32_e32 v237, 10, v90
	v_or_b32_e32 v90, 9, v90
	v_cmp_lt_i32_e32 vcc, v90, v186
	v_cmp_lt_i32_e64 s[10:11], v237, v169
	v_pk_mul_f32 v[86:87], v[238:239], v[248:249]
	v_cndmask_b32_e32 v236, 1.0, v94, vcc
	v_cndmask_b32_e64 v238, 1.0, v95, s[10:11]
	v_mul_f32_e32 v90, v97, v236
	v_mul_f32_e32 v97, v238, v247
	v_mul_f32_e32 v239, v90, v97
	ds_bpermute_b32 v237, v231, v239
	v_mul_f32_e32 v235, v235, v242
	v_mul_f32_e32 v97, v234, v235
	v_cndmask_b32_e64 v93, 0, v93, s[10:11]
	v_cndmask_b32_e32 v92, 0, v92, vcc
	s_waitcnt lgkmcnt(0)
	v_mul_f32_e32 v90, v97, v237
	v_cndmask_b32_e64 v90, v97, v90, s[6:7]
	v_mul_f32_e32 v235, v247, v90
	v_mul_f32_e32 v234, v238, v235
	v_mul_f32_e32 v247, v226, v228
	v_pk_mul_f32 v[94:95], v[92:93], v[234:235]
	v_pk_mul_f32 v[92:93], v[244:245], v[246:247]
	ds_bpermute_b32 v231, v231, v93
	v_mov_b32_e32 v235, v239
	v_pk_mul_f32 v[90:91], v[232:233], v[90:91]
	v_pk_mul_f32 v[232:233], v[234:235], v[236:237]
	v_pk_mul_f32 v[84:85], v[240:241], v[84:85]
	v_pk_mul_f32 v[96:97], v[96:97], v[232:233]
	s_mov_b64 s[10:11], 0
